# NSA loops: mask fast path laid out as the inline fall-through, slow per-key masked path out of line (no taken branches on the common path)
# speedup vs baseline: 1.0043x; 1.0043x over previous
.LBB0_1210:
	s_bitcmp1_b32 s16, 0
	v_lshrrev_b64 v[10:11], v0, v[170:171]
	s_cselect_b32 s27, 0x8c00, 0
	v_and_b32_e32 v10, 1, v10
	v_add_u32_e32 v234, s27, v219
	v_cmp_eq_u32_e32 vcc, 1, v10
	v_cmp_ne_u32_e64 s[0:1], 0, v10
	ds_read_b128 v[82:85], v234
	ds_read_b128 v[142:145], v234 offset:32
	ds_read_b128 v[138:141], v234 offset:64
	ds_read_b128 v[10:13], v234 offset:96
	s_cmp_lg_u64 s[0:1], 0
	s_cselect_b64 s[22:23], -1, 0
	s_and_b64 s[16:17], s[12:13], vcc
	v_lshl_or_b32 v233, v0, 6, v188
	v_cndmask_b32_e64 v169, 0, v168, s[16:17]
	v_add_u32_e32 v81, s27, v220
	s_mov_b64 vcc, s[0:1]
	s_cbranch_vccz .LBB0_1214
	s_waitcnt lgkmcnt(3)
	v_mfma_f32_32x32x16_bf16 v[82:97], v[82:85], v[122:125], 0
	s_waitcnt lgkmcnt(2)
	v_mfma_f32_32x32x16_bf16 v[82:97], v[142:145], v[126:129], v[82:97]
	s_waitcnt lgkmcnt(1)
	v_mfma_f32_32x32x16_bf16 v[82:97], v[138:141], v[98:101], v[82:97]
	ds_read_b128 v[138:141], v234 offset:128
	ds_read_b128 v[142:145], v234 offset:160
	ds_read_b128 v[236:239], v234 offset:192
	ds_read_b128 v[240:243], v234 offset:224
	s_waitcnt lgkmcnt(4)
	v_mfma_f32_32x32x16_bf16 v[82:97], v[10:13], v[102:105], v[82:97]
	s_waitcnt lgkmcnt(3)
	v_mfma_f32_32x32x16_bf16 v[82:97], v[138:141], v[106:109], v[82:97]
	s_cmp_eq_u64 s[14:15], 0
	s_cbranch_scc0 .Lself0_slow
	ds_read_b128 v[138:141], v81 offset:17408
	ds_read_b128 v[10:13], v81 offset:22016
	s_waitcnt lgkmcnt(4)
	v_mfma_f32_32x32x16_bf16 v[82:97], v[142:145], v[110:113], v[82:97]
	s_waitcnt lgkmcnt(3)
	v_mfma_f32_32x32x16_bf16 v[82:97], v[236:239], v[114:117], v[82:97]
	s_waitcnt lgkmcnt(2)
	v_mfma_f32_32x32x16_bf16 v[82:97], v[240:243], v[118:121], v[82:97]
	s_nop 11
	v_cndmask_b32_e64 v237, v231, v82, s[16:17]
	v_cndmask_b32_e64 v238, v231, v83, s[16:17]
	v_cndmask_b32_e64 v239, v231, v84, s[16:17]
	v_cndmask_b32_e64 v240, v231, v85, s[16:17]
	v_cndmask_b32_e64 v142, v231, v86, s[16:17]
	v_cndmask_b32_e64 v143, v231, v87, s[16:17]
	v_cndmask_b32_e64 v144, v231, v88, s[16:17]
	v_cndmask_b32_e64 v145, v231, v89, s[16:17]
	v_cndmask_b32_e64 v244, v231, v90, s[16:17]
	v_cndmask_b32_e64 v241, v231, v91, s[16:17]
	v_cndmask_b32_e64 v242, v231, v92, s[16:17]
	v_cndmask_b32_e64 v243, v231, v93, s[16:17]
	v_cndmask_b32_e64 v90, v231, v94, s[16:17]
	v_cndmask_b32_e64 v91, v231, v95, s[16:17]
	v_cndmask_b32_e64 v92, v231, v96, s[16:17]
	v_max_f32_e32 v0, v237, v238
	v_max3_f32 v0, v0, v239, v240
	v_max3_f32 v0, v0, v142, v143
	v_max3_f32 v0, v0, v144, v145
	v_max3_f32 v0, v0, v244, v241
	v_max3_f32 v0, v0, v242, v243
	v_cndmask_b32_e64 v93, v231, v97, s[16:17]
	v_max3_f32 v0, v0, v90, v91
	v_max3_f32 v0, v0, v92, v93

.Lself0_slow:
	v_cndmask_b32_e64 v0, v230, v233, s[16:17]
	v_cmp_le_u32_e32 vcc, v0, v169
	v_or_b32_e32 v208, 10, v0
	v_or_b32_e32 v209, 11, v0
	v_or_b32_e32 v210, 16, v0
	v_or_b32_e32 v211, 17, v0
	ds_read_b128 v[138:141], v81 offset:17408
	ds_read_b128 v[10:13], v81 offset:22016
	s_waitcnt lgkmcnt(4)
	v_mfma_f32_32x32x16_bf16 v[82:97], v[142:145], v[110:113], v[82:97]
	v_or_b32_e32 v142, 2, v0
	v_or_b32_e32 v143, 3, v0
	v_or_b32_e32 v144, 8, v0
	v_or_b32_e32 v145, 9, v0
	s_waitcnt lgkmcnt(3)
	v_mfma_f32_32x32x16_bf16 v[82:97], v[236:239], v[114:117], v[82:97]
	s_waitcnt lgkmcnt(2)
	v_mfma_f32_32x32x16_bf16 v[82:97], v[240:243], v[118:121], v[82:97]
	s_nop 11
	v_cndmask_b32_e32 v237, v231, v82, vcc
	v_cmp_lt_u32_e32 vcc, v0, v169
	v_or_b32_e32 v82, 18, v0
	s_nop 0
	v_cndmask_b32_e32 v238, v231, v83, vcc
	v_cmp_le_u32_e32 vcc, v142, v169
	s_nop 1
	v_cndmask_b32_e32 v239, v231, v84, vcc
	v_cmp_le_u32_e32 vcc, v143, v169
	s_nop 1
	v_cndmask_b32_e32 v240, v231, v85, vcc
	v_cmp_le_u32_e32 vcc, v144, v169
	s_nop 1
	v_cndmask_b32_e32 v142, v231, v86, vcc
	v_cmp_le_u32_e32 vcc, v145, v169
	s_nop 1
	v_cndmask_b32_e32 v143, v231, v87, vcc
	v_cmp_le_u32_e32 vcc, v208, v169
	s_nop 1
	v_cndmask_b32_e32 v144, v231, v88, vcc
	v_cmp_le_u32_e32 vcc, v209, v169
	s_nop 1
	v_cndmask_b32_e32 v145, v231, v89, vcc
	v_cmp_le_u32_e32 vcc, v210, v169
	s_nop 1
	v_cndmask_b32_e32 v244, v231, v90, vcc
	v_cmp_le_u32_e32 vcc, v211, v169
	s_nop 1
	v_cndmask_b32_e32 v241, v231, v91, vcc
	v_cmp_le_u32_e32 vcc, v82, v169
	v_or_b32_e32 v82, 19, v0
	s_nop 0
	v_cndmask_b32_e32 v242, v231, v92, vcc
	v_cmp_le_u32_e32 vcc, v82, v169
	v_or_b32_e32 v82, 24, v0
	s_nop 0
	v_cndmask_b32_e32 v243, v231, v93, vcc
	v_cmp_le_u32_e32 vcc, v82, v169
	v_or_b32_e32 v82, 25, v0
	s_nop 0
	v_cndmask_b32_e32 v90, v231, v94, vcc
	v_cmp_le_u32_e32 vcc, v82, v169
	v_or_b32_e32 v82, 26, v0
	v_or_b32_e32 v0, 27, v0
	v_cndmask_b32_e32 v91, v231, v95, vcc
	v_cmp_le_u32_e32 vcc, v82, v169
	v_max_f32_e32 v82, v237, v237
	s_nop 0
	v_cndmask_b32_e32 v92, v231, v96, vcc
	v_cmp_le_u32_e32 vcc, v0, v169
	v_max_f32_e32 v0, v238, v238
	v_max_f32_e32 v0, v82, v0
	v_max3_f32 v0, v0, v239, v240
	v_max3_f32 v0, v0, v142, v143
	v_max3_f32 v0, v0, v144, v145
	v_max3_f32 v0, v0, v244, v241
	v_max3_f32 v0, v0, v242, v243
	v_cndmask_b32_e32 v93, v231, v97, vcc
	v_max3_f32 v0, v0, v90, v91
	v_max3_f32 v0, v0, v92, v93
	s_branch .Lself0_join
.Lself1_slow:
	v_or_b32_e32 v0, 32, v233
	v_cndmask_b32_e64 v0, v230, v0, s[16:17]
	v_cmp_le_u32_e32 vcc, v0, v169
	v_or_b32_e32 v14, 2, v0
	v_or_b32_e32 v15, 3, v0
	v_or_b32_e32 v208, 10, v0
	v_or_b32_e32 v209, 11, v0
	s_waitcnt lgkmcnt(2)
	v_mfma_f32_32x32x16_bf16 v[82:97], v[142:145], v[110:113], v[82:97]
	v_or_b32_e32 v142, 8, v0
	v_or_b32_e32 v143, 9, v0
	v_or_b32_e32 v210, 16, v0
	ds_read_b128 v[138:141], v81 offset:17472
	ds_read_b128 v[10:13], v81 offset:22080
	s_waitcnt lgkmcnt(3)
	v_mfma_f32_32x32x16_bf16 v[82:97], v[238:241], v[114:117], v[82:97]
	s_waitcnt lgkmcnt(2)
	v_mfma_f32_32x32x16_bf16 v[82:97], v[242:245], v[118:121], v[82:97]
	s_nop 11
	v_cndmask_b32_e32 v144, v231, v82, vcc
	v_cmp_lt_u32_e32 vcc, v0, v169
	v_or_b32_e32 v82, 17, v0
	s_nop 0
	v_cndmask_b32_e32 v145, v231, v83, vcc
	v_cmp_le_u32_e32 vcc, v14, v169
	s_nop 1
	v_cndmask_b32_e32 v233, v231, v84, vcc
	v_cmp_le_u32_e32 vcc, v15, v169
	s_nop 1
	v_cndmask_b32_e32 v234, v231, v85, vcc
	v_cmp_le_u32_e32 vcc, v142, v169
	s_nop 1
	v_cndmask_b32_e32 v14, v231, v86, vcc
	v_cmp_le_u32_e32 vcc, v143, v169
	s_nop 1
	v_cndmask_b32_e32 v15, v231, v87, vcc
	v_cmp_le_u32_e32 vcc, v208, v169
	s_nop 1
	v_cndmask_b32_e32 v142, v231, v88, vcc
	v_cmp_le_u32_e32 vcc, v209, v169
	s_nop 1
	v_cndmask_b32_e32 v143, v231, v89, vcc
	v_cmp_le_u32_e32 vcc, v210, v169
	s_nop 1
	v_cndmask_b32_e32 v237, v231, v90, vcc
	v_cmp_le_u32_e32 vcc, v82, v169
	v_or_b32_e32 v82, 18, v0
	s_nop 0
	v_cndmask_b32_e32 v238, v231, v91, vcc
	v_cmp_le_u32_e32 vcc, v82, v169
	v_or_b32_e32 v82, 19, v0
	s_nop 0
	v_cndmask_b32_e32 v239, v231, v92, vcc
	v_cmp_le_u32_e32 vcc, v82, v169
	v_or_b32_e32 v82, 24, v0
	s_nop 0
	v_cndmask_b32_e32 v240, v231, v93, vcc
	v_cmp_le_u32_e32 vcc, v82, v169
	v_or_b32_e32 v82, 25, v0
	s_nop 0
	v_cndmask_b32_e32 v90, v231, v94, vcc
	v_cmp_le_u32_e32 vcc, v82, v169
	v_or_b32_e32 v82, 26, v0
	v_or_b32_e32 v0, 27, v0
	v_cndmask_b32_e32 v91, v231, v95, vcc
	v_cmp_le_u32_e32 vcc, v82, v169
	v_max_f32_e32 v82, v144, v144
	s_nop 0
	v_cndmask_b32_e32 v92, v231, v96, vcc
	v_cmp_le_u32_e32 vcc, v0, v169
	v_max_f32_e32 v0, v145, v145
	v_max_f32_e32 v0, v82, v0
	v_max3_f32 v0, v0, v233, v234
	v_max3_f32 v0, v0, v14, v15
	v_max3_f32 v0, v0, v142, v143
	v_max3_f32 v0, v0, v237, v238
	v_max3_f32 v0, v0, v239, v240
	v_cndmask_b32_e32 v93, v231, v97, vcc
	v_max3_f32 v0, v0, v90, v91
	v_max3_f32 v0, v0, v92, v93
	s_branch .Lself1_join

.LBB0_1217:
	s_andn2_b64 vcc, exec, s[22:23]
	s_cbranch_vccnz .LBB0_1221
	s_waitcnt lgkmcnt(3)
	v_mfma_f32_32x32x16_bf16 v[82:97], v[82:85], v[122:125], 0
	s_waitcnt lgkmcnt(2)
	v_mfma_f32_32x32x16_bf16 v[82:97], v[142:145], v[126:129], v[82:97]
	s_waitcnt lgkmcnt(1)
	v_mfma_f32_32x32x16_bf16 v[82:97], v[138:141], v[98:101], v[82:97]
	ds_read_b128 v[138:141], v234 offset:8832
	ds_read_b128 v[142:145], v234 offset:8864
	ds_read_b128 v[238:241], v234 offset:8896
	ds_read_b128 v[242:245], v234 offset:8928
	s_waitcnt lgkmcnt(4)
	v_mfma_f32_32x32x16_bf16 v[82:97], v[10:13], v[102:105], v[82:97]
	s_waitcnt lgkmcnt(3)
	v_mfma_f32_32x32x16_bf16 v[82:97], v[138:141], v[106:109], v[82:97]
	s_cmp_eq_u64 s[14:15], 0
	s_cbranch_scc0 .Lself1_slow
	s_waitcnt lgkmcnt(2)
	v_mfma_f32_32x32x16_bf16 v[82:97], v[142:145], v[110:113], v[82:97]
	ds_read_b128 v[138:141], v81 offset:17472
	ds_read_b128 v[10:13], v81 offset:22080
	s_waitcnt lgkmcnt(3)
	v_mfma_f32_32x32x16_bf16 v[82:97], v[238:241], v[114:117], v[82:97]
	s_waitcnt lgkmcnt(2)
	v_mfma_f32_32x32x16_bf16 v[82:97], v[242:245], v[118:121], v[82:97]
	s_nop 11
	v_cndmask_b32_e64 v144, v231, v82, s[16:17]
	v_cndmask_b32_e64 v145, v231, v83, s[16:17]
	v_cndmask_b32_e64 v233, v231, v84, s[16:17]
	v_cndmask_b32_e64 v234, v231, v85, s[16:17]
	v_cndmask_b32_e64 v14, v231, v86, s[16:17]
	v_cndmask_b32_e64 v15, v231, v87, s[16:17]
	v_cndmask_b32_e64 v142, v231, v88, s[16:17]
	v_cndmask_b32_e64 v143, v231, v89, s[16:17]
	v_cndmask_b32_e64 v237, v231, v90, s[16:17]
	v_cndmask_b32_e64 v238, v231, v91, s[16:17]
	v_cndmask_b32_e64 v239, v231, v92, s[16:17]
	v_cndmask_b32_e64 v240, v231, v93, s[16:17]
	v_cndmask_b32_e64 v90, v231, v94, s[16:17]
	v_cndmask_b32_e64 v91, v231, v95, s[16:17]
	v_cndmask_b32_e64 v92, v231, v96, s[16:17]
	v_max_f32_e32 v0, v144, v145
	v_max3_f32 v0, v0, v233, v234
	v_max3_f32 v0, v0, v14, v15
	v_max3_f32 v0, v0, v142, v143
	v_max3_f32 v0, v0, v237, v238
	v_max3_f32 v0, v0, v239, v240
	v_cndmask_b32_e64 v93, v231, v97, s[16:17]
	v_max3_f32 v0, v0, v90, v91
	v_max3_f32 v0, v0, v92, v93

.LBB0_1238:
	s_bitcmp1_b32 s15, 0
	s_cselect_b32 s0, 0x8c00, 0
	v_add_u32_e32 v245, s0, v219
	ds_read_b128 v[10:13], v245
	ds_read_b128 v[138:141], v245 offset:32
	v_add_u32_e32 v167, s0, v220
	v_lshl_add_u32 v172, v0, 6, v171
	s_waitcnt lgkmcnt(1)
	v_mfma_f32_32x32x16_bf16 v[80:95], v[10:13], v[122:125], 0
	s_waitcnt lgkmcnt(0)
	v_mfma_f32_32x32x16_bf16 v[80:95], v[138:141], v[126:129], v[80:95]
	ds_read_b128 v[10:13], v245 offset:64
	ds_read_b128 v[138:141], v245 offset:96
	s_waitcnt lgkmcnt(1)
	v_mfma_f32_32x32x16_bf16 v[80:95], v[10:13], v[98:101], v[80:95]
	ds_read_b128 v[10:13], v245 offset:128
	ds_read_b128 v[232:235], v245 offset:160
	ds_read_b128 v[236:239], v245 offset:192
	ds_read_b128 v[240:243], v245 offset:224
	s_waitcnt lgkmcnt(4)
	v_mfma_f32_32x32x16_bf16 v[80:95], v[138:141], v[102:105], v[80:95]
	s_waitcnt lgkmcnt(3)
	v_mfma_f32_32x32x16_bf16 v[80:95], v[10:13], v[106:109], v[80:95]
	s_cmp_eq_u64 s[12:13], 0
	s_cselect_b32 s98, s15, 0
	s_cmp_lg_u32 s98, 0
	s_cbranch_scc0 .Lwinf0_slow
	s_waitcnt lgkmcnt(2)
	v_mfma_f32_32x32x16_bf16 v[80:95], v[232:235], v[110:113], v[80:95]
	ds_read_b128 v[138:141], v167 offset:17408
	ds_read_b128 v[10:13], v167 offset:22016
	s_waitcnt lgkmcnt(3)
	v_mfma_f32_32x32x16_bf16 v[80:95], v[236:239], v[114:117], v[80:95]
	s_waitcnt lgkmcnt(2)
	v_mfma_f32_32x32x16_bf16 v[80:95], v[240:243], v[118:121], v[80:95]
	s_nop 11
	v_mov_b32_e32 v143, v80
	v_mov_b32_e32 v144, v81
	v_mov_b32_e32 v145, v82
	v_mov_b32_e32 v232, v83
	v_mov_b32_e32 v233, v84
	v_mov_b32_e32 v234, v85
	v_mov_b32_e32 v235, v86
	v_mov_b32_e32 v236, v87
	v_max_f32_e32 v0, v143, v144
	v_max3_f32 v0, v0, v145, v232
	v_max3_f32 v0, v0, v233, v234
	v_max3_f32 v0, v0, v235, v236
	v_max3_f32 v0, v0, v88, v89
	v_max3_f32 v0, v0, v90, v91
	v_max3_f32 v0, v0, v92, v93
	v_max3_f32 v0, v0, v94, v95

.LBB0_1242:
	s_waitcnt lgkmcnt(3)
	v_mfma_f32_32x32x16_bf16 v[80:95], v[80:83], v[122:125], 0
	s_waitcnt lgkmcnt(2)
	v_mfma_f32_32x32x16_bf16 v[80:95], v[142:145], v[126:129], v[80:95]
	s_waitcnt lgkmcnt(1)
	v_mfma_f32_32x32x16_bf16 v[80:95], v[138:141], v[98:101], v[80:95]
	ds_read_b128 v[138:141], v245 offset:8832
	ds_read_b128 v[142:145], v245 offset:8864
	ds_read_b128 v[248:251], v245 offset:8896
	ds_read_b128 v[208:211], v245 offset:8928
	s_waitcnt lgkmcnt(4)
	v_mfma_f32_32x32x16_bf16 v[80:95], v[10:13], v[102:105], v[80:95]
	s_waitcnt lgkmcnt(3)
	v_mfma_f32_32x32x16_bf16 v[80:95], v[138:141], v[106:109], v[80:95]
	s_cmp_eq_u64 s[12:13], 0
	s_cselect_b32 s98, s15, 1
	s_cmp_lg_u32 s98, 1
	s_cbranch_scc0 .Lwinf1_slow
	ds_read_b128 v[138:141], v167 offset:17472
	ds_read_b128 v[10:13], v167 offset:22080
	s_waitcnt lgkmcnt(4)
	v_mfma_f32_32x32x16_bf16 v[80:95], v[142:145], v[110:113], v[80:95]
	s_waitcnt lgkmcnt(3)
	v_mfma_f32_32x32x16_bf16 v[80:95], v[248:251], v[114:117], v[80:95]
	s_waitcnt lgkmcnt(2)
	v_mfma_f32_32x32x16_bf16 v[80:95], v[208:211], v[118:121], v[80:95]
	s_nop 11
	v_mov_b32_e32 v15, v80
	v_mov_b32_e32 v143, v81
	v_mov_b32_e32 v144, v82
	v_mov_b32_e32 v145, v83
	v_mov_b32_e32 v245, v84
	v_mov_b32_e32 v247, v85
	v_mov_b32_e32 v248, v86
	v_mov_b32_e32 v249, v87
	v_max_f32_e32 v14, v15, v143
	v_max3_f32 v14, v14, v144, v145
	v_max3_f32 v14, v14, v245, v247
	v_max3_f32 v14, v14, v248, v249
	v_max3_f32 v14, v14, v88, v89
	v_max3_f32 v14, v14, v90, v91
	v_max3_f32 v14, v14, v92, v93
	v_max3_f32 v14, v14, v94, v95

.Lwinf0_slow:
	s_movk_i32 s0, 0x200
	v_add_u32_e32 v0, 0xfffffe01, v172
	v_cmp_gt_u32_e32 vcc, s0, v172
	v_add_u32_e32 v145, 0xfffffe02, v172
	v_add_u32_e32 v173, 0xfffffe03, v172
	v_add_u32_e32 v174, 0xfffffe08, v172
	v_add_u32_e32 v175, 0xfffffe09, v172
	s_waitcnt lgkmcnt(2)
	v_mfma_f32_32x32x16_bf16 v[80:95], v[232:235], v[110:113], v[80:95]
	v_add_u32_e32 v208, 0xfffffe0a, v172
	v_add_u32_e32 v209, 0xfffffe0b, v172
	v_add_u32_e32 v210, 0xfffffe10, v172
	v_add_u32_e32 v211, 0xfffffe11, v172
	ds_read_b128 v[138:141], v167 offset:17408
	ds_read_b128 v[10:13], v167 offset:22016
	s_waitcnt lgkmcnt(3)
	v_mfma_f32_32x32x16_bf16 v[80:95], v[236:239], v[114:117], v[80:95]
	s_waitcnt lgkmcnt(2)
	v_mfma_f32_32x32x16_bf16 v[80:95], v[240:243], v[118:121], v[80:95]
	s_nop 11
	v_cndmask_b32_e32 v143, v231, v80, vcc
	v_cmp_lt_u32_e32 vcc, s87, v0
	v_add_u32_e32 v0, 0xfffffe12, v172
	v_max_f32_e32 v80, v143, v143
	v_cndmask_b32_e32 v144, v231, v81, vcc
	v_cmp_lt_u32_e32 vcc, s87, v145
	s_nop 1
	v_cndmask_b32_e32 v145, v231, v82, vcc
	v_cmp_lt_u32_e32 vcc, s87, v173
	s_nop 1
	v_cndmask_b32_e32 v232, v231, v83, vcc
	v_cmp_lt_u32_e32 vcc, s87, v174
	s_nop 1
	v_cndmask_b32_e32 v233, v231, v84, vcc
	v_cmp_lt_u32_e32 vcc, s87, v175
	s_nop 1
	v_cndmask_b32_e32 v234, v231, v85, vcc
	v_cmp_lt_u32_e32 vcc, s87, v208
	s_nop 1
	v_cndmask_b32_e32 v235, v231, v86, vcc
	v_cmp_lt_u32_e32 vcc, s87, v209
	s_nop 1
	v_cndmask_b32_e32 v236, v231, v87, vcc
	v_cmp_lt_u32_e32 vcc, s87, v210
	s_nop 1
	v_cndmask_b32_e32 v88, v231, v88, vcc
	v_cmp_lt_u32_e32 vcc, s87, v211
	s_nop 1
	v_cndmask_b32_e32 v89, v231, v89, vcc
	v_cmp_lt_u32_e32 vcc, s87, v0
	v_add_u32_e32 v0, 0xfffffe13, v172
	s_nop 0
	v_cndmask_b32_e32 v90, v231, v90, vcc
	v_cmp_lt_u32_e32 vcc, s87, v0
	v_add_u32_e32 v0, 0xfffffe18, v172
	s_nop 0
	v_cndmask_b32_e32 v91, v231, v91, vcc
	v_cmp_lt_u32_e32 vcc, s87, v0
	v_add_u32_e32 v0, 0xfffffe19, v172
	s_nop 0
	v_cndmask_b32_e32 v92, v231, v92, vcc
	v_cmp_lt_u32_e32 vcc, s87, v0
	v_add_u32_e32 v0, 0xfffffe1a, v172
	s_nop 0
	v_cndmask_b32_e32 v93, v231, v93, vcc
	v_cmp_lt_u32_e32 vcc, s87, v0
	v_add_u32_e32 v0, 0xfffffe1b, v172
	s_nop 0
	v_cndmask_b32_e32 v94, v231, v94, vcc
	v_cmp_lt_u32_e32 vcc, s87, v0
	v_max_f32_e32 v0, v144, v144
	v_max_f32_e32 v0, v80, v0
	v_max3_f32 v0, v0, v145, v232
	v_max3_f32 v0, v0, v233, v234
	v_max3_f32 v0, v0, v235, v236
	v_max3_f32 v0, v0, v88, v89
	v_max3_f32 v0, v0, v90, v91
	v_cndmask_b32_e32 v95, v231, v95, vcc
	v_max3_f32 v0, v0, v92, v93
	v_max3_f32 v0, v0, v94, v95
	s_branch .Lwinf0_join
.Lwinf1_slow:
	v_add_u32_e32 v14, 0xfffffe20, v172
	v_cmp_lt_u32_e32 vcc, s87, v14
	v_add_u32_e32 v245, 0xfffffe28, v172
	v_add_u32_e32 v247, 0xfffffe29, v172
	v_add_u32_e32 v14, 0xfffffe31, v172
	ds_read_b128 v[138:141], v167 offset:17472
	ds_read_b128 v[10:13], v167 offset:22080
	s_waitcnt lgkmcnt(4)
	v_mfma_f32_32x32x16_bf16 v[80:95], v[142:145], v[110:113], v[80:95]
	v_add_u32_e32 v142, 0xfffffe21, v172
	v_add_u32_e32 v144, 0xfffffe22, v172
	v_add_u32_e32 v145, 0xfffffe23, v172
	s_waitcnt lgkmcnt(3)
	v_mfma_f32_32x32x16_bf16 v[80:95], v[248:251], v[114:117], v[80:95]
	v_add_u32_e32 v248, 0xfffffe2a, v172
	v_add_u32_e32 v249, 0xfffffe2b, v172
	v_add_u32_e32 v250, 0xfffffe30, v172
	s_waitcnt lgkmcnt(2)
	v_mfma_f32_32x32x16_bf16 v[80:95], v[208:211], v[118:121], v[80:95]
	s_nop 11
	v_cndmask_b32_e32 v15, v231, v80, vcc
	v_cmp_lt_u32_e32 vcc, s87, v142
	v_max_f32_e32 v80, v15, v15
	s_nop 0
	v_cndmask_b32_e32 v143, v231, v81, vcc
	v_cmp_lt_u32_e32 vcc, s87, v144
	s_nop 1
	v_cndmask_b32_e32 v144, v231, v82, vcc
	v_cmp_lt_u32_e32 vcc, s87, v145
	s_nop 1
	v_cndmask_b32_e32 v145, v231, v83, vcc
	v_cmp_lt_u32_e32 vcc, s87, v245
	s_nop 1
	v_cndmask_b32_e32 v245, v231, v84, vcc
	v_cmp_lt_u32_e32 vcc, s87, v247
	s_nop 1
	v_cndmask_b32_e32 v247, v231, v85, vcc
	v_cmp_lt_u32_e32 vcc, s87, v248
	s_nop 1
	v_cndmask_b32_e32 v248, v231, v86, vcc
	v_cmp_lt_u32_e32 vcc, s87, v249
	s_nop 1
	v_cndmask_b32_e32 v249, v231, v87, vcc
	v_cmp_lt_u32_e32 vcc, s87, v250
	s_nop 1
	v_cndmask_b32_e32 v88, v231, v88, vcc
	v_cmp_lt_u32_e32 vcc, s87, v14
	v_add_u32_e32 v14, 0xfffffe32, v172
	s_nop 0
	v_cndmask_b32_e32 v89, v231, v89, vcc
	v_cmp_lt_u32_e32 vcc, s87, v14
	v_add_u32_e32 v14, 0xfffffe33, v172
	s_nop 0
	v_cndmask_b32_e32 v90, v231, v90, vcc
	v_cmp_lt_u32_e32 vcc, s87, v14
	v_add_u32_e32 v14, 0xfffffe38, v172
	s_nop 0
	v_cndmask_b32_e32 v91, v231, v91, vcc
	v_cmp_lt_u32_e32 vcc, s87, v14
	v_add_u32_e32 v14, 0xfffffe39, v172
	s_nop 0
	v_cndmask_b32_e32 v92, v231, v92, vcc
	v_cmp_lt_u32_e32 vcc, s87, v14
	v_add_u32_e32 v14, 0xfffffe3a, v172
	s_nop 0
	v_cndmask_b32_e32 v93, v231, v93, vcc
	v_cmp_lt_u32_e32 vcc, s87, v14
	v_add_u32_e32 v14, 0xfffffe3b, v172
	s_nop 0
	v_cndmask_b32_e32 v94, v231, v94, vcc
	v_cmp_lt_u32_e32 vcc, s87, v14
	v_max_f32_e32 v14, v143, v143
	v_max_f32_e32 v14, v80, v14
	v_max3_f32 v14, v14, v144, v145
	v_max3_f32 v14, v14, v245, v247
	v_max3_f32 v14, v14, v248, v249
	v_max3_f32 v14, v14, v88, v89
	v_max3_f32 v14, v14, v90, v91
	v_cndmask_b32_e32 v95, v231, v95, vcc
	v_max3_f32 v14, v14, v92, v93
	v_max3_f32 v14, v14, v94, v95
	s_branch .Lwinf1_join
